# v13
# speedup vs baseline: 1.0031x; 1.0008x over previous
; #define LAS __attribute__((address_space(3)))
; __device__ __forceinline__ void convert_matrix(const Ctx& C, const float* W, int K, int N, bf16* WT, int mode, const float* gs) {
;     LAS float* scr = (LAS float*)(C.lds + C.wave * 16384);
;     const int gw = C.bid * 8 + C.wave, NGW = C.G * 8;
;     const int nblk = N / 32, nitems = (K / 64) * nblk;
;     for (int it = gw; it < nitems; it += NGW) {
;         const int kb = it / nblk, nb = it % nblk, n0 = nb * 32;
;         int drow0 = n0;
;         if (mode == 1) { const int j = n0 < DFF ? n0 : n0 - DFF; drow0 = 256 * (j >> 7) + (j & 127) + (n0 < DFF ? 0 : 128); }
;         transpose_item(W, K, N, WT, kb * 64, n0, drow0, scr, C.lane, gs, mode);
;     }
; }
; __device__ __forceinline__ void convert_layer(const Ctx& C, int li) {
;     unsigned char* wl = C.ws + WS_W + (size_t)li * WL_SIZE;
;     convert_matrix(C, C.in[3] + (size_t)li * D * NPROJ, D, NPROJ, (bf16*)(wl + WL_IN), 2, C.in[2] + (size_t)li * D);
.Lp0_loop:
	s_add_u32 s59, s58, s44
	s_cmp_lt_u32 s59, 33344
	s_cbranch_scc0 .Lp0_nonext
	s_mov_b32 s6, s59
	s_mov_b32 s7, 0
	s_cmp_lt_u32 s59, 26912
	s_cbranch_scc1 .Lp0_lay0_b
	s_sub_u32 s6, s59, 26912
	s_mov_b32 s7, 1

; __device__ __forceinline__ f32x4 mma16(bf16x8 x2, bf16x8 x1, f32x4 acc) { return __builtin_amdgcn_mfma_f32_16x16x32_bf16(x2, x1, acc, 0, 0, 0); }
; __device__ __forceinline__ void skinny_proj(const Ctx& C, const bf16* X, const bf16* Wt, const float* SS, bf16* PROJ) {
;     ...
; #pragma unroll 8
;     for (int ks = 0; ks < D / 32; ++ks) {
;         const bf16x8 a = *(const bf16x8*)(A + ks * 32), b0 = *(const bf16x8*)(W0 + ks * 32), b1 = *(const bf16x8*)(W0 + (size_t)16 * D + ks * 32);
;         acc0 = mma16(b0, a, acc0); acc1 = mma16(b1, a, acc1);
;     }
.LBB0_323:
	v_lshl_add_u64 v[26:27], v[8:9], 0, s[6:7]
	v_add_co_u32_e32 v46, vcc, 0x1600000, v26
	v_lshl_add_u64 v[42:43], v[10:11], 0, s[6:7]
	s_nop 0
	v_addc_co_u32_e32 v47, vcc, 0, v27, vcc
	global_load_dwordx4 v[14:17], v[42:43], off offset:-256
	global_load_dwordx4 v[18:21], v[42:43], off offset:-192
	global_load_dwordx4 v[22:25], v[46:47], off
	v_add_co_u32_e32 v48, vcc, 0x1610000, v26
	s_add_u32 s6, s6, 0x200
	s_nop 0
	v_addc_co_u32_e32 v49, vcc, 0, v27, vcc
	global_load_dwordx4 v[26:29], v[46:47], off offset:64
	global_load_dwordx4 v[30:33], v[48:49], off
	s_addc_u32 s7, s7, 0
	s_cmpk_lg_i32 s6, 0x1000
	s_waitcnt vmcnt(0)
	v_mfma_f32_16x16x32_bf16 v[4:7], v[30:33], v[14:17], v[4:7]
	v_mfma_f32_16x16x32_bf16 v[0:3], v[22:25], v[14:17], v[0:3]
	global_load_dwordx4 v[22:25], v[48:49], off offset:64
	global_load_dwordx4 v[14:17], v[42:43], off offset:-128
	global_load_dwordx4 v[30:33], v[42:43], off offset:-64
	global_load_dwordx4 v[34:37], v[42:43], off
	v_mfma_f32_16x16x32_bf16 v[0:3], v[26:29], v[18:21], v[0:3]
	global_load_dwordx4 v[26:29], v[46:47], off offset:128
	global_load_dwordx4 v[38:41], v[46:47], off offset:192
	s_waitcnt vmcnt(1)
	v_mfma_f32_16x16x32_bf16 v[0:3], v[26:29], v[14:17], v[0:3]
	v_mfma_f32_16x16x32_bf16 v[4:7], v[22:25], v[18:21], v[4:7]
	global_load_dwordx4 v[18:21], v[48:49], off offset:128
	global_load_dwordx4 v[22:25], v[48:49], off offset:192
	s_waitcnt vmcnt(2)
	v_mfma_f32_16x16x32_bf16 v[0:3], v[38:41], v[30:33], v[0:3]
	s_waitcnt vmcnt(1)
	v_mfma_f32_16x16x32_bf16 v[4:7], v[18:21], v[14:17], v[4:7]
	global_load_dwordx4 v[14:17], v[42:43], off offset:64
	global_load_dwordx4 v[18:21], v[42:43], off offset:128
	global_load_dwordx4 v[26:29], v[42:43], off offset:192
	global_load_dwordx4 v[38:41], v[46:47], off offset:256
	s_nop 0
	global_load_dwordx4 v[42:45], v[46:47], off offset:320
	s_waitcnt vmcnt(5)
	v_mfma_f32_16x16x32_bf16 v[4:7], v[22:25], v[30:33], v[4:7]
	global_load_dwordx4 v[22:25], v[48:49], off offset:256
	global_load_dwordx4 v[30:33], v[48:49], off offset:320
	s_waitcnt vmcnt(3)
	v_mfma_f32_16x16x32_bf16 v[0:3], v[38:41], v[34:37], v[0:3]
	s_waitcnt vmcnt(1)
	v_mfma_f32_16x16x32_bf16 v[4:7], v[22:25], v[34:37], v[4:7]
	global_load_dwordx4 v[22:25], v[46:47], off offset:384
	global_load_dwordx4 v[34:37], v[48:49], off offset:384
	v_mfma_f32_16x16x32_bf16 v[0:3], v[42:45], v[14:17], v[0:3]
	s_waitcnt vmcnt(2)
	v_mfma_f32_16x16x32_bf16 v[4:7], v[30:33], v[14:17], v[4:7]
	global_load_dwordx4 v[14:17], v[46:47], off offset:448
	s_waitcnt vmcnt(2)
	v_mfma_f32_16x16x32_bf16 v[0:3], v[22:25], v[18:21], v[0:3]
	global_load_dwordx4 v[22:25], v[48:49], off offset:448
	s_waitcnt vmcnt(2)
	v_mfma_f32_16x16x32_bf16 v[4:7], v[34:37], v[18:21], v[4:7]
	s_waitcnt vmcnt(1)
	v_mfma_f32_16x16x32_bf16 v[0:3], v[14:17], v[26:29], v[0:3]
	s_waitcnt vmcnt(0)
	v_mfma_f32_16x16x32_bf16 v[4:7], v[22:25], v[26:29], v[4:7]
	s_cbranch_scc1 .LBB0_323
; #define LAS __attribute__((address_space(3)))
; __device__ __forceinline__ unsigned pk2(float lo, float hi) { return pg8::cvt_pk_bf16(lo, hi); }
; __device__ __forceinline__ void convert_matrix(const Ctx& C, const float* W, int K, int N, bf16* WT, int mode, const float* gs) {
;     LAS float* scr = (LAS float*)(C.lds + C.wave * 16384);
;     const int gw = C.bid * 8 + C.wave, NGW = C.G * 8;
;     const int nblk = N / 32, nitems = (K / 64) * nblk;
;     for (int it = gw; it < nitems; it += NGW) {
;         const int kb = it / nblk, nb = it % nblk, n0 = nb * 32;
;         int drow0 = n0;
;         if (mode == 1) { const int j = n0 < DFF ? n0 : n0 - DFF; drow0 = 256 * (j >> 7) + (j & 127) + (n0 < DFF ? 0 : 128); }
;         transpose_item(W, K, N, WT, kb * 64, n0, drow0, scr, C.lane, gs, mode);
; __device__ __forceinline__ void skinny_proj(const Ctx& C, const bf16* X, const bf16* Wt, const float* SS, bf16* PROJ) {
;     ...
;     const f32x4* p = (const f32x4*)(SS + (size_t)(r0 + fr) * 32); f32x4 sa = p[0];
; #pragma unroll
;     for (int q = 1; q < 8; ++q) sa = sa + p[q];
;     const float rs = rsqrtf(((sa[0] + sa[1]) + (sa[2] + sa[3])) * (1.0f / D) + EPS);
;     bf16* o = PROJ + (size_t)(r0 + fr) * LDP + NMAIN + 4 * fq;
;     *(v2u*)o = (v2u){pk2(acc0[0] * rs, acc0[1] * rs), pk2(acc0[2] * rs, acc0[3] * rs)};
;     *(v2u*)(o + 16) = (v2u){pk2(acc1[0] * rs, acc1[1] * rs), pk2(acc1[2] * rs, acc1[3] * rs)};
	s_addk_i32 s10, 0xc000
	v_or_b32_e32 v8, s10, v13
	v_add_u32_e32 v42, s11, v8
	v_ashrrev_i32_e32 v43, 31, v42
	v_lshlrev_b64 v[8:9], 7, v[42:43]
	v_lshl_add_u64 v[44:45], v[130:131], 0, v[8:9]
	global_load_dwordx4 v[8:11], v[44:45], off
	global_load_dwordx4 v[14:17], v[44:45], off offset:16
	global_load_dwordx4 v[18:21], v[44:45], off offset:32
	global_load_dwordx4 v[22:25], v[44:45], off offset:48
	global_load_dwordx4 v[26:29], v[44:45], off offset:64
	global_load_dwordx4 v[30:33], v[44:45], off offset:80
	global_load_dwordx4 v[34:37], v[44:45], off offset:96
	global_load_dwordx4 v[38:41], v[44:45], off offset:112
	v_and_b32_e32 v12, 3, v12
	s_movk_i32 s8, 0x2e00
	v_mov_b32_e32 v44, 0x358637bd
	v_mov_b32_e32 v13, 0
	v_lshlrev_b32_e32 v12, 3, v12
	v_mad_i64_i32 v[42:43], s[8:9], v42, s8, v[134:135]
	s_mov_b32 s10, 0x800000
	s_mov_b64 s[6:7], 0x2c00
	v_lshl_add_u64 v[12:13], v[42:43], 0, v[12:13]
	v_lshl_add_u64 v[42:43], v[12:13], 0, s[6:7]
	s_movk_i32 s11, 0x2000
	v_add_co_u32_e32 v12, vcc, s11, v12
	s_waitcnt vmcnt(6)
	v_pk_add_f32 v[10:11], v[10:11], v[16:17]
	v_pk_add_f32 v[8:9], v[8:9], v[14:15]
	s_waitcnt vmcnt(5)
	v_pk_add_f32 v[10:11], v[10:11], v[20:21]
	v_pk_add_f32 v[8:9], v[8:9], v[18:19]
	s_waitcnt vmcnt(4)
	v_pk_add_f32 v[10:11], v[10:11], v[24:25]
	v_pk_add_f32 v[8:9], v[8:9], v[22:23]
	s_waitcnt vmcnt(3)
	v_pk_add_f32 v[10:11], v[10:11], v[28:29]
	v_pk_add_f32 v[8:9], v[8:9], v[26:27]
	s_waitcnt vmcnt(2)
	v_pk_add_f32 v[10:11], v[10:11], v[32:33]
	v_pk_add_f32 v[8:9], v[8:9], v[30:31]
	s_waitcnt vmcnt(1)
	v_pk_add_f32 v[10:11], v[10:11], v[36:37]
	v_pk_add_f32 v[8:9], v[8:9], v[34:35]
	s_waitcnt vmcnt(0)
	v_pk_add_f32 v[10:11], v[10:11], v[40:41]
	v_pk_add_f32 v[8:9], v[8:9], v[38:39]
	v_addc_co_u32_e32 v13, vcc, 0, v13, vcc
	v_pk_mov_b32 v[14:15], v[8:9], v[10:11] op_sel:[1,0]
	v_mov_b32_e32 v9, v11
	v_pk_add_f32 v[8:9], v[14:15], v[8:9]
	s_nop 0
	v_add_f32_e32 v8, v8, v9
	v_fmac_f32_e32 v44, 0x3a000000, v8
	v_mul_f32_e32 v8, 0x4b800000, v44
	v_cmp_gt_f32_e64 s[6:7], s10, v44
	s_nop 1
	v_cndmask_b32_e64 v8, v44, v8, s[6:7]
	v_rsq_f32_e32 v8, v8
	s_nop 0
	v_mul_f32_e32 v9, 0x45800000, v8
	v_cndmask_b32_e64 v8, v8, v9, s[6:7]
	v_pk_mul_f32 v[0:1], v[0:1], v[8:9] op_sel_hi:[1,0]
	v_pk_mul_f32 v[2:3], v[2:3], v[8:9] op_sel_hi:[1,0]
	v_pk_mul_f32 v[4:5], v[4:5], v[8:9] op_sel_hi:[1,0]
	v_pk_mul_f32 v[6:7], v[6:7], v[8:9] op_sel_hi:[1,0]
	v_cvt_pk_bf16_f32 v0, v0, v1
	v_cvt_pk_bf16_f32 v1, v2, v3
	v_cvt_pk_bf16_f32 v2, v4, v5
	v_cvt_pk_bf16_f32 v3, v6, v7
	global_store_dwordx2 v[12:13], v[0:1], off offset:3072
	global_store_dwordx2 v[42:43], v[2:3], off offset:32
	v_writelane_b32 v250, s6, 0
	v_writelane_b32 v250, s7, 1
	v_writelane_b32 v250, s8, 2
	v_writelane_b32 v250, s9, 3
	v_writelane_b32 v250, s10, 4
	v_writelane_b32 v250, s11, 5
	v_writelane_b32 v250, s12, 6
	v_writelane_b32 v250, s13, 7
	v_writelane_b32 v250, s14, 8
	v_writelane_b32 v250, s15, 9
	v_writelane_b32 v250, s16, 10
	v_writelane_b32 v250, s17, 11
	v_writelane_b32 v250, s18, 12
	v_writelane_b32 v250, s19, 13
	v_writelane_b32 v250, s20, 14
	v_writelane_b32 v250, s21, 15
	v_writelane_b32 v250, s22, 16
	v_writelane_b32 v250, s23, 17
	v_writelane_b32 v250, s24, 18
	v_writelane_b32 v250, s25, 19
	v_writelane_b32 v250, s26, 20
	v_writelane_b32 v250, s27, 21
	v_writelane_b32 v250, s28, 22
	v_writelane_b32 v250, s29, 23
	v_writelane_b32 v250, s30, 24
	v_writelane_b32 v250, s31, 25
	v_writelane_b32 v250, s32, 26
	v_writelane_b32 v250, s33, 27
	v_writelane_b32 v250, s34, 28
	v_writelane_b32 v250, s35, 29
	v_writelane_b32 v250, s36, 30
	v_writelane_b32 v250, s37, 31
	v_writelane_b32 v250, s38, 32
	v_writelane_b32 v250, s39, 33
	v_writelane_b32 v250, s40, 34
	v_writelane_b32 v250, s41, 35
	v_writelane_b32 v250, s42, 36
	v_writelane_b32 v250, s43, 37
	v_writelane_b32 v250, s44, 38
	v_writelane_b32 v250, s45, 39
	v_writelane_b32 v250, s46, 40
	v_writelane_b32 v250, s47, 41
	v_writelane_b32 v250, s48, 42
	v_writelane_b32 v250, s49, 43
	v_writelane_b32 v250, s50, 44
	v_writelane_b32 v250, s51, 45
	v_writelane_b32 v250, s52, 46
	v_writelane_b32 v250, s53, 47
	v_writelane_b32 v250, s54, 48
	v_writelane_b32 v250, s55, 49
	v_writelane_b32 v250, s56, 50
	v_writelane_b32 v250, s57, 51
	v_writelane_b32 v250, s58, 52
	v_writelane_b32 v250, s59, 53
	v_writelane_b32 v250, s60, 54
	v_writelane_b32 v250, s61, 55
	v_writelane_b32 v250, s62, 56
	v_writelane_b32 v250, s63, 57
	v_writelane_b32 v250, s64, 58
	v_writelane_b32 v250, s65, 59
	v_writelane_b32 v250, s66, 60
	v_writelane_b32 v250, s67, 61
	v_writelane_b32 v250, s68, 62
	v_writelane_b32 v250, s69, 63
	v_writelane_b32 v251, s70, 0
	v_writelane_b32 v251, s71, 1
	v_writelane_b32 v251, s72, 2
	v_writelane_b32 v251, s73, 3
	v_writelane_b32 v251, s74, 4
	v_writelane_b32 v251, s75, 5
	v_writelane_b32 v251, s76, 6
	v_writelane_b32 v251, s77, 7
	v_writelane_b32 v251, s78, 8
	v_writelane_b32 v251, s79, 9
	s_load_dwordx4 s[24:27], s[0:1], 0x10
	s_load_dwordx2 s[28:29], s[0:1], 0x68
	s_load_dwordx4 s[36:39], s[0:1], 0x70
	s_load_dwordx2 s[30:31], s[0:1], 0x90
	s_load_dwordx4 s[40:43], s[0:1], 0x98
	s_load_dwordx2 s[34:35], s[0:1], 0xa8
	s_load_dwordx2 s[48:49], s[0:1], 0xc0
	s_load_dwordx4 s[64:67], s[0:1], 0x0
	v_readfirstlane_b32 s78, v234
	s_lshr_b32 s78, s78, 6
	s_sub_u32 s58, s2, 128
	s_lshl_b32 s58, s58, 3
	s_add_u32 s58, s58, s78
	s_add_u32 s58, s58, 33344
	s_lshl_b32 s78, s78, 14
	v_and_b32_e32 v1, 63, v234
	v_lshrrev_b32_e32 v6, 5, v1
	v_and_b32_e32 v7, 31, v1
	v_lshlrev_b32_e32 v7, 2, v7
	v_mul_u32_u24_e32 v2, 0x84, v6
	v_add3_u32 v2, s78, v2, v7
	v_and_b32_e32 v4, 7, v1
	v_lshrrev_b32_e32 v8, 3, v1
	v_mul_u32_u24_e32 v3, 0x420, v4
	v_lshlrev_b32_e32 v108, 2, v8
	v_add3_u32 v3, s78, v3, v108
	v_lshlrev_b32_e32 v5, 5, v4
	v_lshlrev_b32_e32 v4, 4, v4
	v_mov_b32_e32 v10, 0
	s_waitcnt lgkmcnt(0)
	s_mov_b32 s6, s58
	s_mov_b32 s7, 0
	s_cmp_lt_u32 s58, 26912
	s_cbranch_scc1 .Lq0_lay0_a
	s_sub_u32 s6, s58, 26912
	s_mov_b32 s7, 1

; #define LAS __attribute__((address_space(3)))
; __device__ __forceinline__ void convert_matrix(const Ctx& C, const float* W, int K, int N, bf16* WT, int mode, const float* gs) {
;     LAS float* scr = (LAS float*)(C.lds + C.wave * 16384);
;     const int gw = C.bid * 8 + C.wave, NGW = C.G * 8;
;     const int nblk = N / 32, nitems = (K / 64) * nblk;
;     for (int it = gw; it < nitems; it += NGW) {
;         const int kb = it / nblk, nb = it % nblk, n0 = nb * 32;
;         int drow0 = n0;
;         if (mode == 1) { const int j = n0 < DFF ? n0 : n0 - DFF; drow0 = 256 * (j >> 7) + (j & 127) + (n0 < DFF ? 0 : 128); }
;         transpose_item(W, K, N, WT, kb * 64, n0, drow0, scr, C.lane, gs, mode);
;     }
; }
; __device__ __forceinline__ void convert_layer(const Ctx& C, int li) {
;     unsigned char* wl = C.ws + WS_W + (size_t)li * WL_SIZE;
;     convert_matrix(C, C.in[3] + (size_t)li * D * NPROJ, D, NPROJ, (bf16*)(wl + WL_IN), 2, C.in[2] + (size_t)li * D);
.Lq0_loop:
	s_add_u32 s59, s58, 1024
	s_cmp_lt_u32 s59, 43584
	s_cbranch_scc0 .Lq0_nonext
	s_mov_b32 s6, s59
	s_mov_b32 s7, 0
	s_cmp_lt_u32 s59, 26912
	s_cbranch_scc1 .Lq0_lay0_b
	s_sub_u32 s6, s59, 26912
	s_mov_b32 s7, 1

; __device__ __forceinline__ f32x4 mma16(bf16x8 x2, bf16x8 x1, f32x4 acc) { return __builtin_amdgcn_mfma_f32_16x16x32_bf16(x2, x1, acc, 0, 0, 0); }
; __device__ __forceinline__ void skinny_proj(const Ctx& C, const bf16* X, const bf16* Wt, const float* SS, bf16* PROJ) {
;     ...
; #pragma unroll 8
;     for (int ks = 0; ks < D / 32; ++ks) {
;         const bf16x8 a = *(const bf16x8*)(A + ks * 32), b0 = *(const bf16x8*)(W0 + ks * 32), b1 = *(const bf16x8*)(W0 + (size_t)16 * D + ks * 32);
;         acc0 = mma16(b0, a, acc0); acc1 = mma16(b1, a, acc1);
;     }
.LBB0_1411:
	v_lshl_add_u64 v[28:29], v[12:13], 0, s[12:13]
	v_add_co_u32_e32 v48, vcc, 0x8000000, v28
	v_lshl_add_u64 v[44:45], v[10:11], 0, s[12:13]
	s_nop 0
	v_addc_co_u32_e32 v49, vcc, 0, v29, vcc
	global_load_dwordx4 v[16:19], v[44:45], off
	global_load_dwordx4 v[20:23], v[44:45], off offset:64
	global_load_dwordx4 v[24:27], v[48:49], off
	v_add_co_u32_e32 v50, vcc, 0x8010000, v28
	s_add_u32 s12, s12, 0x200
	s_nop 0
	v_addc_co_u32_e32 v51, vcc, 0, v29, vcc
	global_load_dwordx4 v[28:31], v[48:49], off offset:64
	global_load_dwordx4 v[32:35], v[50:51], off
	s_addc_u32 s13, s13, 0
	s_cmpk_lg_i32 s12, 0x1000
	s_waitcnt vmcnt(0)
	v_mfma_f32_16x16x32_bf16 v[4:7], v[32:35], v[16:19], v[4:7]
	v_mfma_f32_16x16x32_bf16 v[0:3], v[24:27], v[16:19], v[0:3]
	global_load_dwordx4 v[24:27], v[50:51], off offset:64
	global_load_dwordx4 v[16:19], v[44:45], off offset:128
	global_load_dwordx4 v[32:35], v[44:45], off offset:192
	global_load_dwordx4 v[36:39], v[44:45], off offset:256
	v_mfma_f32_16x16x32_bf16 v[0:3], v[28:31], v[20:23], v[0:3]
	global_load_dwordx4 v[28:31], v[48:49], off offset:128
	global_load_dwordx4 v[40:43], v[48:49], off offset:192
	s_waitcnt vmcnt(1)
	v_mfma_f32_16x16x32_bf16 v[0:3], v[28:31], v[16:19], v[0:3]
	v_mfma_f32_16x16x32_bf16 v[4:7], v[24:27], v[20:23], v[4:7]
	global_load_dwordx4 v[20:23], v[50:51], off offset:128
	global_load_dwordx4 v[24:27], v[50:51], off offset:192
	s_waitcnt vmcnt(2)
	v_mfma_f32_16x16x32_bf16 v[0:3], v[40:43], v[32:35], v[0:3]
	s_waitcnt vmcnt(1)
	v_mfma_f32_16x16x32_bf16 v[4:7], v[20:23], v[16:19], v[4:7]
	global_load_dwordx4 v[16:19], v[44:45], off offset:320
	global_load_dwordx4 v[20:23], v[44:45], off offset:384
	global_load_dwordx4 v[28:31], v[44:45], off offset:448
	global_load_dwordx4 v[40:43], v[48:49], off offset:256
	s_nop 0
	global_load_dwordx4 v[44:47], v[48:49], off offset:320
	s_waitcnt vmcnt(5)
	v_mfma_f32_16x16x32_bf16 v[4:7], v[24:27], v[32:35], v[4:7]
	global_load_dwordx4 v[24:27], v[50:51], off offset:256
	global_load_dwordx4 v[32:35], v[50:51], off offset:320
	s_waitcnt vmcnt(3)
	v_mfma_f32_16x16x32_bf16 v[0:3], v[40:43], v[36:39], v[0:3]
	s_waitcnt vmcnt(1)
	v_mfma_f32_16x16x32_bf16 v[4:7], v[24:27], v[36:39], v[4:7]
	global_load_dwordx4 v[24:27], v[48:49], off offset:384
	global_load_dwordx4 v[36:39], v[50:51], off offset:384
	v_mfma_f32_16x16x32_bf16 v[0:3], v[44:47], v[16:19], v[0:3]
	s_waitcnt vmcnt(2)
	v_mfma_f32_16x16x32_bf16 v[4:7], v[32:35], v[16:19], v[4:7]
	global_load_dwordx4 v[16:19], v[48:49], off offset:448
	s_waitcnt vmcnt(2)
	v_mfma_f32_16x16x32_bf16 v[0:3], v[24:27], v[20:23], v[0:3]
	global_load_dwordx4 v[24:27], v[50:51], off offset:448
	s_waitcnt vmcnt(2)
	v_mfma_f32_16x16x32_bf16 v[4:7], v[36:39], v[20:23], v[4:7]
	s_waitcnt vmcnt(1)
	v_mfma_f32_16x16x32_bf16 v[0:3], v[16:19], v[28:31], v[0:3]
	s_waitcnt vmcnt(0)
	v_mfma_f32_16x16x32_bf16 v[4:7], v[24:27], v[28:31], v[4:7]
	s_cbranch_scc1 .LBB0_1411
; #define LAS __attribute__((address_space(3)))
; __device__ __forceinline__ unsigned pk2(float lo, float hi) { return pg8::cvt_pk_bf16(lo, hi); }
; __device__ __forceinline__ void convert_matrix(const Ctx& C, const float* W, int K, int N, bf16* WT, int mode, const float* gs) {
;     LAS float* scr = (LAS float*)(C.lds + C.wave * 16384);
;     const int gw = C.bid * 8 + C.wave, NGW = C.G * 8;
;     const int nblk = N / 32, nitems = (K / 64) * nblk;
;     for (int it = gw; it < nitems; it += NGW) {
;         const int kb = it / nblk, nb = it % nblk, n0 = nb * 32;
;         int drow0 = n0;
;         if (mode == 1) { const int j = n0 < DFF ? n0 : n0 - DFF; drow0 = 256 * (j >> 7) + (j & 127) + (n0 < DFF ? 0 : 128); }
;         transpose_item(W, K, N, WT, kb * 64, n0, drow0, scr, C.lane, gs, mode);
; __device__ __forceinline__ void skinny_proj(const Ctx& C, const bf16* X, const bf16* Wt, const float* SS, bf16* PROJ) {
;     ...
;     const f32x4* p = (const f32x4*)(SS + (size_t)(r0 + fr) * 32); f32x4 sa = p[0];
; #pragma unroll
;     for (int q = 1; q < 8; ++q) sa = sa + p[q];
;     const float rs = rsqrtf(((sa[0] + sa[1]) + (sa[2] + sa[3])) * (1.0f / D) + EPS);
;     bf16* o = PROJ + (size_t)(r0 + fr) * LDP + NMAIN + 4 * fq;
;     *(v2u*)o = (v2u){pk2(acc0[0] * rs, acc0[1] * rs), pk2(acc0[2] * rs, acc0[3] * rs)};
;     *(v2u*)(o + 16) = (v2u){pk2(acc1[0] * rs, acc1[1] * rs), pk2(acc1[2] * rs, acc1[3] * rs)};
	v_lshlrev_b64 v[10:11], 7, v[8:9]
	v_lshl_add_u64 v[44:45], s[20:21], 0, v[10:11]
	global_load_dwordx4 v[10:13], v[44:45], off
	global_load_dwordx4 v[16:19], v[44:45], off offset:16
	global_load_dwordx4 v[20:23], v[44:45], off offset:32
	global_load_dwordx4 v[24:27], v[44:45], off offset:48
	global_load_dwordx4 v[28:31], v[44:45], off offset:64
	global_load_dwordx4 v[32:35], v[44:45], off offset:80
	global_load_dwordx4 v[36:39], v[44:45], off offset:96
	global_load_dwordx4 v[40:43], v[44:45], off offset:112
	v_mov_b32_e32 v46, 0x358637bd
	s_movk_i32 s12, 0x2e00
	v_mov_b64_e32 v[44:45], s[16:17]
	s_mov_b32 s14, 0x800000
	v_mad_i64_i32 v[8:9], s[12:13], v8, s12, v[44:45]
	v_lshlrev_b32_e32 v14, 3, v14
	v_mov_b32_e32 v15, 0
	s_mov_b64 s[10:11], 0x2c00
	s_movk_i32 s15, 0x2000
	v_lshl_add_u64 v[8:9], v[8:9], 0, v[14:15]
	v_lshl_add_u64 v[14:15], v[8:9], 0, s[10:11]
	v_add_co_u32_e32 v8, vcc, s15, v8
	s_waitcnt vmcnt(6)
	v_pk_add_f32 v[12:13], v[12:13], v[18:19]
	v_pk_add_f32 v[10:11], v[10:11], v[16:17]
	s_waitcnt vmcnt(5)
	v_pk_add_f32 v[12:13], v[12:13], v[22:23]
	v_pk_add_f32 v[10:11], v[10:11], v[20:21]
	s_waitcnt vmcnt(4)
	v_pk_add_f32 v[12:13], v[12:13], v[26:27]
	v_pk_add_f32 v[10:11], v[10:11], v[24:25]
	s_waitcnt vmcnt(3)
	v_pk_add_f32 v[12:13], v[12:13], v[30:31]
	v_pk_add_f32 v[10:11], v[10:11], v[28:29]
	s_waitcnt vmcnt(2)
	v_pk_add_f32 v[12:13], v[12:13], v[34:35]
	v_pk_add_f32 v[10:11], v[10:11], v[32:33]
	s_waitcnt vmcnt(1)
	v_pk_add_f32 v[12:13], v[12:13], v[38:39]
	v_pk_add_f32 v[10:11], v[10:11], v[36:37]
	s_waitcnt vmcnt(0)
	v_pk_add_f32 v[12:13], v[12:13], v[42:43]
	v_pk_add_f32 v[10:11], v[10:11], v[40:41]
	v_addc_co_u32_e32 v9, vcc, 0, v9, vcc
	v_pk_mov_b32 v[16:17], v[10:11], v[12:13] op_sel:[1,0]
	v_mov_b32_e32 v11, v13
	v_pk_add_f32 v[10:11], v[16:17], v[10:11]
	s_nop 0
	v_add_f32_e32 v10, v10, v11
	v_fmac_f32_e32 v46, 0x3a000000, v10
	v_mul_f32_e32 v10, 0x4b800000, v46
	v_cmp_gt_f32_e64 s[12:13], s14, v46
	s_nop 1
	v_cndmask_b32_e64 v10, v46, v10, s[12:13]
	v_rsq_f32_e32 v10, v10
	s_nop 0
	v_mul_f32_e32 v11, 0x45800000, v10
	v_cndmask_b32_e64 v10, v10, v11, s[12:13]
	v_pk_mul_f32 v[0:1], v[0:1], v[10:11] op_sel_hi:[1,0]
	v_pk_mul_f32 v[2:3], v[2:3], v[10:11] op_sel_hi:[1,0]
	v_pk_mul_f32 v[4:5], v[4:5], v[10:11] op_sel_hi:[1,0]
	v_pk_mul_f32 v[6:7], v[6:7], v[10:11] op_sel_hi:[1,0]
	v_cvt_pk_bf16_f32 v0, v0, v1
	v_cvt_pk_bf16_f32 v1, v2, v3
	v_cvt_pk_bf16_f32 v2, v4, v5
	v_cvt_pk_bf16_f32 v3, v6, v7
	global_store_dwordx2 v[8:9], v[0:1], off offset:3072
	global_store_dwordx2 v[14:15], v[2:3], off offset:32
	v_writelane_b32 v250, s6, 0
	v_writelane_b32 v250, s7, 1
	v_writelane_b32 v250, s8, 2
	v_writelane_b32 v250, s9, 3
	v_writelane_b32 v250, s10, 4
	v_writelane_b32 v250, s11, 5
	v_writelane_b32 v250, s12, 6
	v_writelane_b32 v250, s13, 7
	v_writelane_b32 v250, s14, 8
	v_writelane_b32 v250, s15, 9
	v_writelane_b32 v250, s16, 10
	v_writelane_b32 v250, s17, 11
	v_writelane_b32 v250, s18, 12
	v_writelane_b32 v250, s19, 13
	v_writelane_b32 v250, s20, 14
	v_writelane_b32 v250, s21, 15
	v_writelane_b32 v250, s22, 16
	v_writelane_b32 v250, s23, 17
	v_writelane_b32 v250, s24, 18
	v_writelane_b32 v250, s25, 19
	v_writelane_b32 v250, s26, 20
	v_writelane_b32 v250, s27, 21
	v_writelane_b32 v250, s28, 22
	v_writelane_b32 v250, s29, 23
	v_writelane_b32 v250, s30, 24
	v_writelane_b32 v250, s31, 25
	v_writelane_b32 v250, s32, 26
	v_writelane_b32 v250, s33, 27
	v_writelane_b32 v250, s34, 28
	v_writelane_b32 v250, s35, 29
	v_writelane_b32 v250, s36, 30
	v_writelane_b32 v250, s37, 31
	v_writelane_b32 v250, s38, 32
	v_writelane_b32 v250, s39, 33
	v_writelane_b32 v250, s40, 34
	v_writelane_b32 v250, s41, 35
	v_writelane_b32 v250, s42, 36
	v_writelane_b32 v250, s43, 37
	v_writelane_b32 v250, s44, 38
	v_writelane_b32 v250, s45, 39
	v_writelane_b32 v250, s46, 40
	v_writelane_b32 v250, s47, 41
	v_writelane_b32 v250, s48, 42
	v_writelane_b32 v250, s49, 43
	v_writelane_b32 v250, s50, 44
	v_writelane_b32 v250, s51, 45
	v_writelane_b32 v250, s52, 46
	v_writelane_b32 v250, s53, 47
	v_writelane_b32 v250, s54, 48
	v_writelane_b32 v250, s55, 49
	v_writelane_b32 v250, s56, 50
	v_writelane_b32 v250, s57, 51
	v_writelane_b32 v250, s58, 52
	v_writelane_b32 v250, s59, 53
	v_writelane_b32 v250, s60, 54
	v_writelane_b32 v250, s61, 55
	v_writelane_b32 v250, s62, 56
	v_writelane_b32 v250, s63, 57
	v_writelane_b32 v250, s64, 58
	v_writelane_b32 v250, s65, 59
	v_writelane_b32 v250, s66, 60
	v_writelane_b32 v250, s67, 61
	v_writelane_b32 v250, s68, 62
	v_writelane_b32 v250, s69, 63
	v_writelane_b32 v251, s70, 0
	v_writelane_b32 v251, s71, 1
	v_writelane_b32 v251, s72, 2
	v_writelane_b32 v251, s73, 3
	v_writelane_b32 v251, s74, 4
	v_writelane_b32 v251, s75, 5
	v_writelane_b32 v251, s76, 6
	v_writelane_b32 v251, s77, 7
	v_writelane_b32 v251, s78, 8
	v_writelane_b32 v251, s79, 9
	s_load_dwordx4 s[24:27], s[0:1], 0x10
	s_load_dwordx2 s[28:29], s[0:1], 0x68
	s_load_dwordx4 s[36:39], s[0:1], 0x70
	s_load_dwordx2 s[30:31], s[0:1], 0x90
	s_load_dwordx4 s[40:43], s[0:1], 0x98
	s_load_dwordx2 s[34:35], s[0:1], 0xa8
	s_load_dwordx2 s[48:49], s[0:1], 0xc0
	s_load_dwordx4 s[64:67], s[0:1], 0x0
	v_readfirstlane_b32 s78, v234
	s_lshr_b32 s78, s78, 6
	s_sub_u32 s58, s2, 128
	s_lshl_b32 s58, s58, 3
	s_add_u32 s58, s58, s78
	s_add_u32 s58, s58, 43584
	s_lshl_b32 s78, s78, 14
	v_and_b32_e32 v1, 63, v234
	v_lshrrev_b32_e32 v6, 5, v1
	v_and_b32_e32 v7, 31, v1
	v_lshlrev_b32_e32 v7, 2, v7
	v_mul_u32_u24_e32 v2, 0x84, v6
	v_add3_u32 v2, s78, v2, v7
	v_and_b32_e32 v4, 7, v1
	v_lshrrev_b32_e32 v8, 3, v1
	v_mul_u32_u24_e32 v3, 0x420, v4
	v_lshlrev_b32_e32 v108, 2, v8
	v_add3_u32 v3, s78, v3, v108
	v_lshlrev_b32_e32 v5, 5, v4
	v_lshlrev_b32_e32 v4, 4, v4
	v_mov_b32_e32 v10, 0
	s_waitcnt lgkmcnt(0)
	s_mov_b32 s6, s58
	s_mov_b32 s7, 0
	s_cmp_lt_u32 s58, 26912
	s_cbranch_scc1 .Lr0_lay0_a
	s_sub_u32 s6, s58, 26912
	s_mov_b32 s7, 1

; #define LAS __attribute__((address_space(3)))
; __device__ __forceinline__ unsigned pk2(float lo, float hi) { return pg8::cvt_pk_bf16(lo, hi); }
; #define LDS_WAIT() asm volatile("s_waitcnt lgkmcnt(0)" ::: "memory")
; #pragma unroll 8
;     for (int i = 0; i < 32; ++i) { const int kk = 2 * i + (lane >> 5); const float sc = gs ? gs[k0 + kk] : 1.0f; scr[kk * 33 + (lane & 31)] = __builtin_nontemporal_load(W + (size_t)(k0 + kk) * N + n0 + (lane & 31)) * sc; }
;     LDS_WAIT();
;     const int c = lane & 7;
; #pragma unroll
;     for (int j = 0; j < 4; ++j) { const int n = (lane >> 3) + 8 * j; const LAS float* s = scr + (8 * c) * 33 + n;
;         v4u o; o.x = pk2(s[0 * 33], s[1 * 33]); o.y = pk2(s[2 * 33], s[3 * 33]); o.z = pk2(s[4 * 33], s[5 * 33]); o.w = pk2(s[6 * 33], s[7 * 33]);
;         const int drow = mode == 2 ? inproj_col(n0 + n) : drow0 + n;
;         *(v4u*)(WT + (size_t)drow * K + k0 + 8 * c) = o; }
;     LDS_WAIT();
; }
; __device__ __forceinline__ void convert_matrix(const Ctx& C, const float* W, int K, int N, bf16* WT, int mode, const float* gs) {
;     LAS float* scr = (LAS float*)(C.lds + C.wave * 16384);
;     const int gw = C.bid * 8 + C.wave, NGW = C.G * 8;
;     const int nblk = N / 32, nitems = (K / 64) * nblk;
;     for (int it = gw; it < nitems; it += NGW) {
;         const int kb = it / nblk, nb = it % nblk, n0 = nb * 32;
;         int drow0 = n0;
;         if (mode == 1) { const int j = n0 < DFF ? n0 : n0 - DFF; drow0 = 256 * (j >> 7) + (j & 127) + (n0 < DFF ? 0 : 128); }
;         transpose_item(W, K, N, WT, kb * 64, n0, drow0, scr, C.lane, gs, mode);
;     }
; __device__ __forceinline__ void xcd_barrier(const XcdBarrier& b) {
;     asm volatile("s_waitcnt vmcnt(0)" ::: "memory");
;     __syncthreads();
;     if (threadIdx.x == 0) {
;         unsigned* bar = b.bar;
;         __builtin_amdgcn_s_waitcnt(0);
;         unsigned nloc = b.st[0], nx = b.st[1];
;         if (nloc == 0u) { xcd_barrier_complete(bar, b.x, nloc, nx); b.st[0] = nloc; b.st[1] = nx; }
.Lr0_havegs:
	s_waitcnt lgkmcnt(12)
	v_pk_mul_f32 v[52:53], v[52:53], v[12:13]
	v_pk_mul_f32 v[54:55], v[54:55], v[14:15]
	v_pk_mul_f32 v[56:57], v[56:57], v[16:17]
	v_pk_mul_f32 v[58:59], v[58:59], v[18:19]
	v_cvt_pk_bf16_f32 v84, v52, v53
	v_cvt_pk_bf16_f32 v85, v54, v55
	v_cvt_pk_bf16_f32 v86, v56, v57
	v_cvt_pk_bf16_f32 v87, v58, v59
	global_store_dwordx4 v100, v[84:87], s[50:51]
	s_waitcnt lgkmcnt(8)
	v_pk_mul_f32 v[60:61], v[60:61], v[12:13]
	v_pk_mul_f32 v[62:63], v[62:63], v[14:15]
	v_pk_mul_f32 v[64:65], v[64:65], v[16:17]
	v_pk_mul_f32 v[66:67], v[66:67], v[18:19]
	v_cvt_pk_bf16_f32 v88, v60, v61
	v_cvt_pk_bf16_f32 v89, v62, v63
	v_cvt_pk_bf16_f32 v90, v64, v65
	v_cvt_pk_bf16_f32 v91, v66, v67
	global_store_dwordx4 v101, v[88:91], s[50:51]
	s_waitcnt lgkmcnt(4)
	v_pk_mul_f32 v[68:69], v[68:69], v[12:13]
	v_pk_mul_f32 v[70:71], v[70:71], v[14:15]
	v_pk_mul_f32 v[72:73], v[72:73], v[16:17]
	v_pk_mul_f32 v[74:75], v[74:75], v[18:19]
	v_cvt_pk_bf16_f32 v92, v68, v69
	v_cvt_pk_bf16_f32 v93, v70, v71
	v_cvt_pk_bf16_f32 v94, v72, v73
	v_cvt_pk_bf16_f32 v95, v74, v75
	global_store_dwordx4 v102, v[92:95], s[50:51]
	s_waitcnt lgkmcnt(0)
	v_pk_mul_f32 v[76:77], v[76:77], v[12:13]
	v_pk_mul_f32 v[78:79], v[78:79], v[14:15]
	v_pk_mul_f32 v[80:81], v[80:81], v[16:17]
	v_pk_mul_f32 v[82:83], v[82:83], v[18:19]
	v_cvt_pk_bf16_f32 v96, v76, v77
	v_cvt_pk_bf16_f32 v97, v78, v79
	v_cvt_pk_bf16_f32 v98, v80, v81
	v_cvt_pk_bf16_f32 v99, v82, v83
	global_store_dwordx4 v103, v[96:99], s[50:51]
	s_mov_b32 s50, s70
	s_mov_b32 s51, s71
	s_mov_b32 s52, s72
	s_mov_b32 s53, s73
	s_mov_b32 s54, s74
	s_mov_b32 s55, s75
	s_mov_b32 s56, s76
	s_mov_b32 s57, s77
	s_mov_b32 s58, s59
	s_cmp_eq_u32 s63, 1
	s_cbranch_scc1 .Lr0_loop
	s_waitcnt vmcnt(0)
	v_readlane_b32 s6, v250, 0
	v_readlane_b32 s7, v250, 1
	v_readlane_b32 s8, v250, 2
	v_readlane_b32 s9, v250, 3
	v_readlane_b32 s10, v250, 4
	v_readlane_b32 s11, v250, 5
	v_readlane_b32 s12, v250, 6
	v_readlane_b32 s13, v250, 7
	v_readlane_b32 s14, v250, 8
	v_readlane_b32 s15, v250, 9
	v_readlane_b32 s16, v250, 10
	v_readlane_b32 s17, v250, 11
	v_readlane_b32 s18, v250, 12
	v_readlane_b32 s19, v250, 13
	v_readlane_b32 s20, v250, 14
	v_readlane_b32 s21, v250, 15
	v_readlane_b32 s22, v250, 16
	v_readlane_b32 s23, v250, 17
	v_readlane_b32 s24, v250, 18
	v_readlane_b32 s25, v250, 19
	v_readlane_b32 s26, v250, 20
	v_readlane_b32 s27, v250, 21
	v_readlane_b32 s28, v250, 22
	v_readlane_b32 s29, v250, 23
	v_readlane_b32 s30, v250, 24
	v_readlane_b32 s31, v250, 25
	v_readlane_b32 s32, v250, 26
	v_readlane_b32 s33, v250, 27
	v_readlane_b32 s34, v250, 28
	v_readlane_b32 s35, v250, 29
	v_readlane_b32 s36, v250, 30
	v_readlane_b32 s37, v250, 31
	v_readlane_b32 s38, v250, 32
	v_readlane_b32 s39, v250, 33
	v_readlane_b32 s40, v250, 34
	v_readlane_b32 s41, v250, 35
	v_readlane_b32 s42, v250, 36
	v_readlane_b32 s43, v250, 37
	v_readlane_b32 s44, v250, 38
	v_readlane_b32 s45, v250, 39
	v_readlane_b32 s46, v250, 40
	v_readlane_b32 s47, v250, 41
	v_readlane_b32 s48, v250, 42
	v_readlane_b32 s49, v250, 43
	v_readlane_b32 s50, v250, 44
	v_readlane_b32 s51, v250, 45
	v_readlane_b32 s52, v250, 46
	v_readlane_b32 s53, v250, 47
	v_readlane_b32 s54, v250, 48
	v_readlane_b32 s55, v250, 49
	v_readlane_b32 s56, v250, 50
	v_readlane_b32 s57, v250, 51
	v_readlane_b32 s58, v250, 52
	v_readlane_b32 s59, v250, 53
	v_readlane_b32 s60, v250, 54
	v_readlane_b32 s61, v250, 55
	v_readlane_b32 s62, v250, 56
	v_readlane_b32 s63, v250, 57
	v_readlane_b32 s64, v250, 58
	v_readlane_b32 s65, v250, 59
	v_readlane_b32 s66, v250, 60
	v_readlane_b32 s67, v250, 61
	v_readlane_b32 s68, v250, 62
	v_readlane_b32 s69, v250, 63
	v_readlane_b32 s70, v251, 0
	v_readlane_b32 s71, v251, 1
	v_readlane_b32 s72, v251, 2
	v_readlane_b32 s73, v251, 3
	v_readlane_b32 s74, v251, 4
	v_readlane_b32 s75, v251, 5
	v_readlane_b32 s76, v251, 6
	v_readlane_b32 s77, v251, 7
	v_readlane_b32 s78, v251, 8
	v_readlane_b32 s79, v251, 9
.LBB0_1413:
	s_mov_b32 s16, 0
	s_getreg_b32 s10, hwreg(HW_REG_XCC_ID, 0, 4)
	s_waitcnt vmcnt(0)
	s_waitcnt vmcnt(0)
	s_barrier
	s_and_saveexec_b64 s[12:13], s[4:5]
	s_cbranch_execz .LBB0_1465
	s_load_dwordx2 s[14:15], s[0:1], 0xc0
	s_ashr_i32 s17, s16, 31
	s_lshl_b64 s[18:19], s[16:17], 2
	s_waitcnt vmcnt(0) expcnt(0) lgkmcnt(0)
	s_add_u32 s11, s14, s18
	s_addc_u32 s15, s15, s19
	s_add_u32 s14, s11, 0x25d00000
	s_addc_u32 s15, s15, 0
	s_add_i32 s11, s16, 0
	s_add_i32 s11, s11, 0x23f00
	v_mov_b32_e32 v0, s11
	ds_read_b32 v2, v0
	ds_read_b32 v0, v0 offset:4
	s_and_b32 s10, s10, 15
	s_waitcnt lgkmcnt(1)
	v_cmp_ne_u32_e32 vcc, 0, v2
	s_cbranch_vccnz .LBB0_1429
	s_add_u32 s16, s14, 0x1000
	s_addc_u32 s17, s15, 0
	s_add_u32 s18, s14, 0x1100
	s_addc_u32 s19, s15, 0
	s_add_u32 s20, s14, 0x1200
	s_addc_u32 s21, s15, 0
	s_mul_i32 s30, s47, s94
	s_add_u32 s22, s14, 0x1300
	s_mul_i32 s30, s30, s46
	s_addc_u32 s23, s15, 0
	s_mov_b32 s31, 1
	v_mov_b32_e32 v16, 0
	s_branch .LBB0_1417
